# adds: prompt k/v-window tail of P4 (workgroups 0..63): every load of the element requested before the first wait (three dependent round trips -> one)
# speedup vs baseline: 1.0109x; 1.0109x over previous
; __device__ __forceinline__ float bf2f(bf16_t h) { return __uint_as_float((unsigned)h << 16); }
; __global__ void __launch_bounds__(512, 2) fwd_mega(Params prm) {
;     ...
;         { const bf16_t* P = (const bf16_t*)(ws + WS_P); const float* rope = (const float*)(ws + WS_ROPE);
;           for (int i = F.bid * 512 + F.tid; i < 32768; i += F.G * 512) { const int pos = SP - 128 + (i >> 8), cc = i & 255, d = cc & 63; const bf16_t* row = P + (size_t)pos * NIN;
;               float kv = bf2f(row[C_AK + cc]);
;               if (d < 16) { const float ko = bf2f(row[C_AK + (cc ^ 8)]); const float cs = rope[pos * 16 + (d & 7)], sn = rope[pos * 16 + 8 + (d & 7)]; kv = d < 8 ? kv * cs - ko * sn : kv * cs + ko * sn; }
;               F.out[O_KWP + i] = kv; F.out[O_VWP + i] = bf2f(row[C_AV + cc]); } }
.LBB0_619:
	v_ashrrev_i32_e32 v1, 8, v0
	v_add_u32_e32 v15, 0x1f80, v1
	v_mad_i64_i32 v[12:13], s[12:13], v15, s7, v[6:7]
	v_lshl_add_u64 v[10:11], v[12:13], 0, v[8:9]
	global_load_ushort v1, v[10:11], off offset:2048
	global_load_ushort v18, v[10:11], off offset:2560
	s_and_saveexec_b64 s[12:13], s[0:1]
	v_lshl_or_b32 v16, v15, 4, v14
	v_lshl_add_u64 v[12:13], v[2:3], 1, v[12:13]
	v_ashrrev_i32_e32 v17, 31, v16
	v_lshl_add_u64 v[16:17], v[16:17], 2, s[48:49]
	global_load_ushort v12, v[12:13], off offset:2048
	global_load_dword v13, v[16:17], off offset:32
	global_load_dword v15, v[16:17], off
	s_or_b64 exec, exec, s[12:13]
	s_waitcnt vmcnt(0)
	v_lshlrev_b32_e32 v1, 16, v1
	s_and_saveexec_b64 s[12:13], s[0:1]
	v_lshlrev_b32_e32 v12, 16, v12
	v_mul_f32_e32 v12, v13, v12
	v_cndmask_b32_e64 v12, v12, -v12, s[2:3]
	v_fmac_f32_e32 v12, v15, v1
	v_mov_b32_e32 v1, v12
	s_or_b64 exec, exec, s[12:13]
	v_add_co_u32_e32 v10, vcc, 0x20000, v4
	v_add_u32_e32 v0, s6, v0
	s_nop 0
	v_addc_co_u32_e32 v11, vcc, 0, v5, vcc
	v_cmp_lt_i32_e32 vcc, s14, v0
	global_store_dword v[4:5], v1, off
	s_or_b64 s[10:11], vcc, s[10:11]
	v_lshl_add_u64 v[4:5], v[4:5], 0, s[8:9]
	v_lshlrev_b32_e32 v1, 16, v18
	global_store_dword v[10:11], v1, off
	s_andn2_b64 exec, exec, s[10:11]
	s_cbranch_execz .LBB0_621
	s_branch .LBB0_619
